# ssd_pass2 z-gate loads moved in front of the Y MFMA section (right after the barrier) into registers dead until the end of the head iteration
# speedup vs baseline: 1.0053x; 1.0026x over previous
; __device__ __forceinline__ float bflo(unsigned u) { return __uint_as_float(u << 16); }
; __device__ __forceinline__ float bfhi(unsigned u) { return __uint_as_float(u & 0xFFFF0000u); }
; __device__ __forceinline__ float siluf_(float x) { return x * __builtin_amdgcn_rcpf(1.f + __expf(-x)); }
; __device__ __forceinline__ f32x16 mfma32(bf16x8 a, bf16x8 b, f32x16 c) { return __builtin_amdgcn_mfma_f32_32x32x16_bf16(a, b, c, 0, 0, 0); }
; __device__ __forceinline__ void ssd_pass2(const Params& p, int layer, int task, char* sm) {
;     ...
;     const int nks = nS >> 4;
;     for (int ks = 0; ks < nks; ks++) {
;       bf16x8 xf = *(const bf16x8*)(sXT + (32 * wc2 + r32) * 136 + ks * 16 + 8 * h5);
;       bf16x8 mf = *(const bf16x8*)(sM + (32 * wr + r32) * 136 + ks * 16 + 8 * h5);
;       yd = mfma32(xf, mf, yd);
;     }
;     {
; #pragma unroll
;       for (int ks = 0; ks < 8; ks++) {
;         bf16x8 cf = *(const bf16x8*)(sC + (32 * wr + r32) * 136 + ks * 16 + 8 * h5);
;         yo = mfma32(pfr[ks], cf, yo);
;       }
;     }
;     {
;       const int lp = 32 * wr + r32; const int l = 64 * lh + lp; const size_t tok = tok0 + l;
;       const float eo = __expf(sAcs[l * 8 + hh]);
;       float ss = 0.f;
; #pragma unroll
;       for (int q = 0; q < 4; q++) {
;         const int pp = 32 * wc2 + 8 * q + 4 * h5;
;         uint2 zz = *(const uint2*)(p.P + tok * PW + C_SSZ + hd * 64 + pp);
;         float v0 = (yd[4 * q] + eo * yo[4 * q]) * siluf_(bflo(zz.x));
;         float v1 = (yd[4 * q + 1] + eo * yo[4 * q + 1]) * siluf_(bfhi(zz.x));
;         float v2 = (yd[4 * q + 2] + eo * yo[4 * q + 2]) * siluf_(bflo(zz.y));
.LBB0_1774:
	v_mov_b32_e32 v16, v145
	v_mov_b32_e32 v17, v145
	v_mov_b32_e32 v18, v145
	v_mov_b32_e32 v19, v145
	v_mov_b32_e32 v20, v145
	v_mov_b32_e32 v21, v145
	v_mov_b32_e32 v22, v145
	v_mov_b32_e32 v23, v145
	v_mov_b32_e32 v24, v145
	v_mov_b32_e32 v25, v145
	v_mov_b32_e32 v26, v145
	v_mov_b32_e32 v27, v145
	v_mov_b32_e32 v28, v145
	v_mov_b32_e32 v29, v145
	v_mov_b32_e32 v30, v145
	v_mov_b32_e32 v31, v145
	s_waitcnt lgkmcnt(0)
	s_barrier
	v_lshl_add_u64 v[250:251], s[68:69], 1, v[156:157]
	global_load_dwordx2 v[198:199], v[250:251], off
	global_load_dwordx2 v[200:201], v[250:251], off offset:16
	global_load_dwordx2 v[204:205], v[250:251], off offset:32
	global_load_dwordx2 v[210:211], v[250:251], off offset:48
	s_mov_b32 s74, 0
	v_mov_b64_e32 v[46:47], v[30:31]
	v_mov_b32_e32 v144, v249
	v_mov_b32_e32 v160, v248
	v_mov_b64_e32 v[44:45], v[28:29]
	v_mov_b64_e32 v[42:43], v[26:27]
	v_mov_b64_e32 v[40:41], v[24:25]
	v_mov_b64_e32 v[38:39], v[22:23]
	v_mov_b64_e32 v[36:37], v[20:21]
	v_mov_b64_e32 v[34:35], v[18:19]
	v_mov_b64_e32 v[32:33], v[16:17]
.LBB0_1775:
	ds_read_b128 v[162:165], v144
	ds_read_b128 v[166:169], v160
	s_add_i32 s74, s74, 1
	v_add_u32_e32 v160, 32, v160
	s_cmp_ge_u32 s74, s85
	v_add_u32_e32 v144, 32, v144
	s_waitcnt lgkmcnt(0)
	v_mfma_f32_32x32x16_bf16 v[32:47], v[162:165], v[166:169], v[32:47]
	s_cbranch_scc0 .LBB0_1775
	v_cvt_pk_bf16_f32 v108, v108, v109
	v_cvt_pk_bf16_f32 v109, v110, v111
	v_cvt_pk_bf16_f32 v110, v100, v101
	v_cvt_pk_bf16_f32 v111, v102, v103
	v_cvt_pk_bf16_f32 v103, v94, v95
	v_cvt_pk_bf16_f32 v95, v86, v87
	v_cvt_pk_bf16_f32 v87, v78, v79
	v_cvt_pk_bf16_f32 v79, v70, v71
	v_cvt_pk_bf16_f32 v71, v62, v63
	v_cvt_pk_bf16_f32 v62, v52, v53
	v_cvt_pk_bf16_f32 v63, v54, v55
	v_cvt_pk_bf16_f32 v52, v56, v57
	v_cvt_pk_bf16_f32 v53, v58, v59
	v_cvt_pk_bf16_f32 v54, v48, v49
	v_cvt_pk_bf16_f32 v55, v50, v51
	ds_read_b128 v[48:51], v188 offset:8192
	ds_read_b128 v[56:59], v188 offset:8224
	s_waitcnt lgkmcnt(1)
	v_mfma_f32_32x32x16_bf16 v[16:31], v[108:111], v[48:51], v[16:31]
	v_cvt_pk_bf16_f32 v100, v104, v105
	v_cvt_pk_bf16_f32 v101, v106, v107
	v_cvt_pk_bf16_f32 v102, v92, v93
	v_cvt_pk_bf16_f32 v92, v96, v97
	v_cvt_pk_bf16_f32 v93, v98, v99
	v_cvt_pk_bf16_f32 v94, v84, v85
	ds_read_b128 v[48:51], v188 offset:8256
	s_waitcnt lgkmcnt(1)
	v_mfma_f32_32x32x16_bf16 v[16:31], v[100:103], v[56:59], v[16:31]
	v_cvt_pk_bf16_f32 v84, v88, v89
	v_cvt_pk_bf16_f32 v85, v90, v91
	v_cvt_pk_bf16_f32 v86, v76, v77
	v_cvt_pk_bf16_f32 v76, v80, v81
	v_cvt_pk_bf16_f32 v77, v82, v83
	v_cvt_pk_bf16_f32 v78, v68, v69
	v_cvt_pk_bf16_f32 v68, v72, v73
	s_waitcnt lgkmcnt(0)
	v_mfma_f32_32x32x16_bf16 v[16:31], v[92:95], v[48:51], v[16:31]
	ds_read_b128 v[48:51], v188 offset:8288
	v_cvt_pk_bf16_f32 v69, v74, v75
	v_cvt_pk_bf16_f32 v70, v60, v61
	v_cvt_pk_bf16_f32 v60, v64, v65
	v_cvt_pk_bf16_f32 v61, v66, v67
	s_lshl_b32 s68, s68, 1
	s_waitcnt lgkmcnt(0)
	v_mfma_f32_32x32x16_bf16 v[16:31], v[84:87], v[48:51], v[16:31]
	ds_read_b128 v[48:51], v188 offset:8320
	s_waitcnt lgkmcnt(0)
	v_mfma_f32_32x32x16_bf16 v[16:31], v[76:79], v[48:51], v[16:31]
	ds_read_b128 v[48:51], v188 offset:8352
	s_waitcnt lgkmcnt(0)
	v_mfma_f32_32x32x16_bf16 v[16:31], v[68:71], v[48:51], v[16:31]
	ds_read_b128 v[48:51], v188 offset:8384
	s_waitcnt lgkmcnt(0)
	v_mfma_f32_32x32x16_bf16 v[16:31], v[60:63], v[48:51], v[16:31]
	ds_read_b128 v[48:51], v188 offset:8416
	s_waitcnt lgkmcnt(0)
	v_mfma_f32_32x32x16_bf16 v[16:31], v[52:55], v[48:51], v[16:31]
	v_lshl_add_u64 v[50:51], v[156:157], 0, s[68:69]
	v_lshl_add_u32 v48, s78, 2, v246
	ds_read_b32 v48, v48
	s_waitcnt lgkmcnt(0)
	v_mul_f32_e32 v48, 0x3fb8aa3b, v48
	v_exp_f32_e32 v48, v48
	s_waitcnt vmcnt(3)
	v_mov_b32_e32 v52, v198
	v_mov_b32_e32 v53, v199
	v_lshlrev_b32_e32 v54, 16, v52
	v_mul_f32_e32 v49, 0xbfb8aa3b, v54
	v_exp_f32_e32 v49, v49
	v_and_b32_e32 v55, 0xffff0000, v52
	v_add_f32_e32 v49, 1.0, v49
	v_pk_fma_f32 v[16:17], v[16:17], v[48:49], v[32:33] op_sel_hi:[1,0,1]
	v_mul_f32_e32 v32, 0xbfb8aa3b, v55
	v_exp_f32_e32 v32, v32
	v_rcp_f32_e32 v56, v49
	v_add_f32_e32 v32, 1.0, v32
	v_rcp_f32_e32 v57, v32
	s_nop 0
	v_pk_mul_f32 v[32:33], v[56:57], v[54:55]
	s_nop 0
	v_pk_mul_f32 v[16:17], v[16:17], v[32:33]
	v_lshlrev_b32_e32 v32, 16, v53
	v_mul_f32_e32 v49, 0xbfb8aa3b, v32
	v_exp_f32_e32 v49, v49
	v_and_b32_e32 v33, 0xffff0000, v53
	v_add_f32_e32 v49, 1.0, v49
	v_pk_fma_f32 v[18:19], v[18:19], v[48:49], v[34:35] op_sel_hi:[1,0,1]
	v_mul_f32_e32 v34, 0xbfb8aa3b, v33
	v_exp_f32_e32 v34, v34
	v_rcp_f32_e32 v52, v49
	v_pk_fma_f32 v[20:21], v[20:21], v[48:49], v[36:37] op_sel_hi:[1,0,1]
	v_pk_fma_f32 v[22:23], v[22:23], v[48:49], v[38:39] op_sel_hi:[1,0,1]
	v_add_f32_e32 v34, 1.0, v34
	v_rcp_f32_e32 v53, v34
	v_cvt_pk_bf16_f32 v34, v16, v17
	v_pk_fma_f32 v[24:25], v[24:25], v[48:49], v[40:41] op_sel_hi:[1,0,1]
	v_pk_fma_f32 v[28:29], v[28:29], v[48:49], v[44:45] op_sel_hi:[1,0,1]
	v_pk_mul_f32 v[32:33], v[52:53], v[32:33]
	s_nop 0
	v_pk_mul_f32 v[18:19], v[18:19], v[32:33]
	v_lshl_add_u64 v[32:33], v[158:159], 0, s[68:69]
	v_cvt_pk_bf16_f32 v35, v18, v19
	global_store_dwordx2 v[32:33], v[34:35], off offset:2048
	s_waitcnt vmcnt(3)
; __device__ __forceinline__ float bflo(unsigned u) { return __uint_as_float(u << 16); }
; __device__ __forceinline__ float bfhi(unsigned u) { return __uint_as_float(u & 0xFFFF0000u); }
; __device__ __forceinline__ float siluf_(float x) { return x * __builtin_amdgcn_rcpf(1.f + __expf(-x)); }
; __device__ __forceinline__ void ssd_pass2(const Params& p, int layer, int task, char* sm) {
;     ...
;       for (int q = 0; q < 4; q++) {
;         const int pp = 32 * wc2 + 8 * q + 4 * h5;
;         uint2 zz = *(const uint2*)(p.P + tok * PW + C_SSZ + hd * 64 + pp);
;         float v0 = (yd[4 * q] + eo * yo[4 * q]) * siluf_(bflo(zz.x));
;         float v1 = (yd[4 * q + 1] + eo * yo[4 * q + 1]) * siluf_(bfhi(zz.x));
;         float v2 = (yd[4 * q + 2] + eo * yo[4 * q + 2]) * siluf_(bflo(zz.y));
;         float v3 = (yd[4 * q + 3] + eo * yo[4 * q + 3]) * siluf_(bfhi(zz.y));
;         ss += v0 * v0 + v1 * v1 + v2 * v2 + v3 * v3;
;         *(uint2*)(p.Y + tok * YW + Y_SSD + hd * 64 + pp) = make_uint2(pk2(v0, v1), pk2(v2, v3));
;       }
;       sSsq[lp * 32 + hh * 4 + wc2 * 2 + h5] = ss;
;     }
	s_nop 3
	v_mov_b32_e32 v34, v200
	v_mov_b32_e32 v35, v201
	v_lshlrev_b32_e32 v52, 16, v34
	v_and_b32_e32 v53, 0xffff0000, v34
	v_mul_f32_e32 v34, 0xbfb8aa3b, v52
	v_exp_f32_e32 v34, v34
	s_nop 0
	v_add_f32_e32 v34, 1.0, v34
	v_rcp_f32_e32 v54, v34
	v_mul_f32_e32 v34, 0xbfb8aa3b, v53
	v_exp_f32_e32 v34, v34
	s_nop 0
	v_add_f32_e32 v34, 1.0, v34
	v_rcp_f32_e32 v55, v34
	v_lshlrev_b32_e32 v34, 16, v35
	v_and_b32_e32 v35, 0xffff0000, v35
	v_pk_mul_f32 v[36:37], v[54:55], v[52:53]
	s_nop 0
	v_pk_mul_f32 v[20:21], v[20:21], v[36:37]
	v_mul_f32_e32 v36, 0xbfb8aa3b, v34
	v_mul_f32_e32 v37, 0xbfb8aa3b, v35
	v_exp_f32_e32 v36, v36
	v_exp_f32_e32 v37, v37
	v_add_f32_e32 v36, 1.0, v36
	v_add_f32_e32 v37, 1.0, v37
	v_rcp_f32_e32 v36, v36
	v_rcp_f32_e32 v37, v37
	s_nop 0
	v_pk_mul_f32 v[34:35], v[36:37], v[34:35]
	s_nop 0
	v_pk_mul_f32 v[22:23], v[22:23], v[34:35]
	v_mov_b32_e32 v34, v16
	v_mov_b32_e32 v16, v17
	v_mov_b32_e32 v17, v21
	v_mov_b32_e32 v35, v20
	v_pk_mul_f32 v[16:17], v[16:17], v[16:17]
	s_nop 0
	v_pk_fma_f32 v[16:17], v[34:35], v[34:35], v[16:17]
	v_mov_b32_e32 v34, v18
	v_mov_b32_e32 v35, v22
	v_pk_fma_f32 v[16:17], v[34:35], v[34:35], v[16:17]
	v_mov_b32_e32 v18, v19
	v_mov_b32_e32 v19, v23
	v_pk_fma_f32 v[16:17], v[18:19], v[18:19], v[16:17]
	v_cvt_pk_bf16_f32 v18, v20, v21
	v_cvt_pk_bf16_f32 v19, v22, v23
	global_store_dwordx2 v[32:33], v[18:19], off offset:2064
	v_add_f32_e32 v16, v16, v17
	s_waitcnt vmcnt(3)
	s_nop 3
	v_mov_b32_e32 v18, v204
	v_mov_b32_e32 v19, v205
	v_lshlrev_b32_e32 v20, 16, v18
	v_and_b32_e32 v21, 0xffff0000, v18
	v_mul_f32_e32 v18, 0xbfb8aa3b, v20
	v_exp_f32_e32 v18, v18
	s_nop 0
	v_add_f32_e32 v18, 1.0, v18
	v_rcp_f32_e32 v22, v18
	v_mul_f32_e32 v18, 0xbfb8aa3b, v21
	v_exp_f32_e32 v18, v18
	s_nop 0
	v_add_f32_e32 v18, 1.0, v18
	v_rcp_f32_e32 v23, v18
	v_lshlrev_b32_e32 v18, 16, v19
	v_and_b32_e32 v19, 0xffff0000, v19
	v_pk_mul_f32 v[20:21], v[22:23], v[20:21]
	v_mul_f32_e32 v22, 0xbfb8aa3b, v18
	v_mul_f32_e32 v23, 0xbfb8aa3b, v19
	v_exp_f32_e32 v22, v22
	v_exp_f32_e32 v23, v23
	v_pk_mul_f32 v[20:21], v[24:25], v[20:21]
	v_pk_fma_f32 v[24:25], v[26:27], v[48:49], v[42:43] op_sel_hi:[1,0,1]
	v_add_f32_e32 v22, 1.0, v22
	v_add_f32_e32 v23, 1.0, v23
	v_rcp_f32_e32 v22, v22
	v_rcp_f32_e32 v23, v23
	s_nop 0
	v_pk_mul_f32 v[18:19], v[22:23], v[18:19]
	s_nop 0
	v_pk_mul_f32 v[18:19], v[24:25], v[18:19]
	v_cvt_pk_bf16_f32 v22, v20, v21
	v_cvt_pk_bf16_f32 v23, v18, v19
	global_store_dwordx2 v[32:33], v[22:23], off offset:2080
	s_waitcnt vmcnt(3)
	s_nop 3
	v_mov_b32_e32 v22, v210
	v_mov_b32_e32 v23, v211
	v_lshlrev_b32_e32 v24, 16, v22
	v_and_b32_e32 v25, 0xffff0000, v22
	v_mul_f32_e32 v22, 0xbfb8aa3b, v24
	v_exp_f32_e32 v22, v22
	s_nop 0
	v_add_f32_e32 v22, 1.0, v22
	v_rcp_f32_e32 v26, v22
	v_mul_f32_e32 v22, 0xbfb8aa3b, v25
	v_exp_f32_e32 v22, v22
	s_nop 0
	v_add_f32_e32 v22, 1.0, v22
	v_rcp_f32_e32 v27, v22
	v_lshlrev_b32_e32 v22, 16, v23
	v_and_b32_e32 v23, 0xffff0000, v23
	v_pk_mul_f32 v[24:25], v[26:27], v[24:25]
	v_mul_f32_e32 v26, 0xbfb8aa3b, v22
	v_mul_f32_e32 v27, 0xbfb8aa3b, v23
	v_exp_f32_e32 v26, v26
	v_exp_f32_e32 v27, v27
	v_pk_mul_f32 v[24:25], v[28:29], v[24:25]
	v_pk_fma_f32 v[28:29], v[30:31], v[48:49], v[46:47] op_sel_hi:[1,0,1]
	v_add_f32_e32 v26, 1.0, v26
	v_add_f32_e32 v27, 1.0, v27
	v_rcp_f32_e32 v26, v26
	v_rcp_f32_e32 v27, v27
	s_nop 0
	v_pk_mul_f32 v[22:23], v[26:27], v[22:23]
	v_mov_b32_e32 v26, v20
	v_mov_b32_e32 v20, v21
	v_mov_b32_e32 v21, v25
	v_pk_mul_f32 v[22:23], v[28:29], v[22:23]
	v_mov_b32_e32 v27, v24
	v_pk_mul_f32 v[20:21], v[20:21], v[20:21]
	v_cvt_pk_bf16_f32 v17, v22, v23
	v_pk_fma_f32 v[20:21], v[26:27], v[26:27], v[20:21]
	v_mov_b32_e32 v26, v18
	v_mov_b32_e32 v27, v22
	v_pk_fma_f32 v[20:21], v[26:27], v[26:27], v[20:21]
	v_mov_b32_e32 v18, v19
	v_mov_b32_e32 v19, v23
	v_pk_fma_f32 v[18:19], v[18:19], v[18:19], v[20:21]
	s_nop 0
	v_add_f32_e32 v16, v16, v18
	v_add_f32_e32 v18, v16, v19
	v_cvt_pk_bf16_f32 v16, v24, v25
	global_store_dwordx2 v[32:33], v[16:17], off offset:2096
	v_lshl_add_u32 v16, s78, 4, v247
	s_add_i32 s78, s78, 1
	s_cmp_eq_u32 s78, 8
	ds_write_b32 v16, v18 offset:60416
	s_cbranch_scc0 .LBB0_1623
	s_branch .LBB0_1784

; __device__ __forceinline__ float bflo(unsigned u) { return __uint_as_float(u << 16); }
; __device__ __forceinline__ float bfhi(unsigned u) { return __uint_as_float(u & 0xFFFF0000u); }
; __device__ __forceinline__ float siluf_(float x) { return x * __builtin_amdgcn_rcpf(1.f + __expf(-x)); }
; __device__ __forceinline__ f32x16 mfma32(bf16x8 a, bf16x8 b, f32x16 c) { return __builtin_amdgcn_mfma_f32_32x32x16_bf16(a, b, c, 0, 0, 0); }
; __device__ __forceinline__ void ssd_pass2(const Params& p, int layer, int task, char* sm) {
;     ...
;     const int nks = nS >> 4;
;     for (int ks = 0; ks < nks; ks++) {
;       bf16x8 xf = *(const bf16x8*)(sXT + (32 * wc2 + r32) * 136 + ks * 16 + 8 * h5);
;       bf16x8 mf = *(const bf16x8*)(sM + (32 * wr + r32) * 136 + ks * 16 + 8 * h5);
;       yd = mfma32(xf, mf, yd);
;     }
;     {
; #pragma unroll
;       for (int ks = 0; ks < 8; ks++) {
;         bf16x8 cf = *(const bf16x8*)(sC + (32 * wr + r32) * 136 + ks * 16 + 8 * h5);
;         yo = mfma32(pfr[ks], cf, yo);
;       }
;     }
;     {
;       const int lp = 32 * wr + r32; const int l = 64 * lh + lp; const size_t tok = tok0 + l;
;       const float eo = __expf(sAcs[l * 8 + hh]);
;       float ss = 0.f;
; #pragma unroll
;       for (int q = 0; q < 4; q++) {
;         const int pp = 32 * wc2 + 8 * q + 4 * h5;
;         uint2 zz = *(const uint2*)(p.P + tok * PW + C_SSZ + hd * 64 + pp);
;         float v0 = (yd[4 * q] + eo * yo[4 * q]) * siluf_(bflo(zz.x));
;         float v1 = (yd[4 * q + 1] + eo * yo[4 * q + 1]) * siluf_(bfhi(zz.x));
;         float v2 = (yd[4 * q + 2] + eo * yo[4 * q + 2]) * siluf_(bflo(zz.y));
.LBB0_2023:
	v_mov_b32_e32 v16, v145
	v_mov_b32_e32 v17, v145
	v_mov_b32_e32 v18, v145
	v_mov_b32_e32 v19, v145
	v_mov_b32_e32 v20, v145
	v_mov_b32_e32 v21, v145
	v_mov_b32_e32 v22, v145
	v_mov_b32_e32 v23, v145
	v_mov_b32_e32 v24, v145
	v_mov_b32_e32 v25, v145
	v_mov_b32_e32 v26, v145
	v_mov_b32_e32 v27, v145
	v_mov_b32_e32 v28, v145
	v_mov_b32_e32 v29, v145
	v_mov_b32_e32 v30, v145
	v_mov_b32_e32 v31, v145
	s_waitcnt lgkmcnt(0)
	s_barrier
	v_lshl_add_u64 v[250:251], s[68:69], 1, v[156:157]
	global_load_dwordx2 v[198:199], v[250:251], off
	global_load_dwordx2 v[200:201], v[250:251], off offset:16
	global_load_dwordx2 v[204:205], v[250:251], off offset:32
	global_load_dwordx2 v[210:211], v[250:251], off offset:48
	s_mov_b32 s78, 0
	v_mov_b64_e32 v[46:47], v[30:31]
	v_mov_b32_e32 v144, v249
	v_mov_b32_e32 v160, v248
	v_mov_b64_e32 v[44:45], v[28:29]
	v_mov_b64_e32 v[42:43], v[26:27]
	v_mov_b64_e32 v[40:41], v[24:25]
	v_mov_b64_e32 v[38:39], v[22:23]
	v_mov_b64_e32 v[36:37], v[20:21]
	v_mov_b64_e32 v[34:35], v[18:19]
	v_mov_b64_e32 v[32:33], v[16:17]
.LBB0_2024:
	ds_read_b128 v[162:165], v144
	ds_read_b128 v[166:169], v160
	s_add_i32 s78, s78, 1
	v_add_u32_e32 v160, 32, v160
	s_cmp_ge_u32 s78, s85
	v_add_u32_e32 v144, 32, v144
	s_waitcnt lgkmcnt(0)
	v_mfma_f32_32x32x16_bf16 v[32:47], v[162:165], v[166:169], v[32:47]
	s_cbranch_scc0 .LBB0_2024
	v_cvt_pk_bf16_f32 v108, v108, v109
	v_cvt_pk_bf16_f32 v109, v110, v111
	v_cvt_pk_bf16_f32 v110, v100, v101
	v_cvt_pk_bf16_f32 v111, v102, v103
	v_cvt_pk_bf16_f32 v103, v94, v95
	v_cvt_pk_bf16_f32 v95, v86, v87
	v_cvt_pk_bf16_f32 v87, v78, v79
	v_cvt_pk_bf16_f32 v79, v70, v71
	v_cvt_pk_bf16_f32 v71, v62, v63
	v_cvt_pk_bf16_f32 v62, v52, v53
	v_cvt_pk_bf16_f32 v63, v54, v55
	v_cvt_pk_bf16_f32 v52, v56, v57
	v_cvt_pk_bf16_f32 v53, v58, v59
	v_cvt_pk_bf16_f32 v54, v48, v49
	v_cvt_pk_bf16_f32 v55, v50, v51
	ds_read_b128 v[48:51], v188 offset:8192
	ds_read_b128 v[56:59], v188 offset:8224
	s_waitcnt lgkmcnt(1)
	v_mfma_f32_32x32x16_bf16 v[16:31], v[108:111], v[48:51], v[16:31]
	v_cvt_pk_bf16_f32 v100, v104, v105
	v_cvt_pk_bf16_f32 v101, v106, v107
	v_cvt_pk_bf16_f32 v102, v92, v93
	v_cvt_pk_bf16_f32 v92, v96, v97
	v_cvt_pk_bf16_f32 v93, v98, v99
	v_cvt_pk_bf16_f32 v94, v84, v85
	ds_read_b128 v[48:51], v188 offset:8256
	s_waitcnt lgkmcnt(1)
	v_mfma_f32_32x32x16_bf16 v[16:31], v[100:103], v[56:59], v[16:31]
	v_cvt_pk_bf16_f32 v84, v88, v89
	v_cvt_pk_bf16_f32 v85, v90, v91
	v_cvt_pk_bf16_f32 v86, v76, v77
	v_cvt_pk_bf16_f32 v76, v80, v81
	v_cvt_pk_bf16_f32 v77, v82, v83
	v_cvt_pk_bf16_f32 v78, v68, v69
	v_cvt_pk_bf16_f32 v68, v72, v73
	s_waitcnt lgkmcnt(0)
	v_mfma_f32_32x32x16_bf16 v[16:31], v[92:95], v[48:51], v[16:31]
	ds_read_b128 v[48:51], v188 offset:8288
	v_cvt_pk_bf16_f32 v69, v74, v75
	v_cvt_pk_bf16_f32 v70, v60, v61
	v_cvt_pk_bf16_f32 v60, v64, v65
	v_cvt_pk_bf16_f32 v61, v66, v67
	s_lshl_b32 s68, s68, 1
	s_waitcnt lgkmcnt(0)
	v_mfma_f32_32x32x16_bf16 v[16:31], v[84:87], v[48:51], v[16:31]
	ds_read_b128 v[48:51], v188 offset:8320
	s_waitcnt lgkmcnt(0)
	v_mfma_f32_32x32x16_bf16 v[16:31], v[76:79], v[48:51], v[16:31]
	ds_read_b128 v[48:51], v188 offset:8352
	s_waitcnt lgkmcnt(0)
	v_mfma_f32_32x32x16_bf16 v[16:31], v[68:71], v[48:51], v[16:31]
	ds_read_b128 v[48:51], v188 offset:8384
	s_waitcnt lgkmcnt(0)
	v_mfma_f32_32x32x16_bf16 v[16:31], v[60:63], v[48:51], v[16:31]
	ds_read_b128 v[48:51], v188 offset:8416
	s_waitcnt lgkmcnt(0)
	v_mfma_f32_32x32x16_bf16 v[16:31], v[52:55], v[48:51], v[16:31]
	v_lshl_add_u64 v[50:51], v[156:157], 0, s[68:69]
	v_lshl_add_u32 v48, s86, 2, v246
	ds_read_b32 v48, v48
	s_waitcnt lgkmcnt(0)
	v_mul_f32_e32 v48, 0x3fb8aa3b, v48
	v_exp_f32_e32 v48, v48
	s_waitcnt vmcnt(3)
	v_mov_b32_e32 v52, v198
	v_mov_b32_e32 v53, v199
	v_lshlrev_b32_e32 v54, 16, v52
	v_mul_f32_e32 v49, 0xbfb8aa3b, v54
	v_exp_f32_e32 v49, v49
	v_and_b32_e32 v55, 0xffff0000, v52
	v_add_f32_e32 v49, 1.0, v49
	v_pk_fma_f32 v[16:17], v[16:17], v[48:49], v[32:33] op_sel_hi:[1,0,1]
	v_mul_f32_e32 v32, 0xbfb8aa3b, v55
	v_exp_f32_e32 v32, v32
	v_rcp_f32_e32 v56, v49
	v_add_f32_e32 v32, 1.0, v32
	v_rcp_f32_e32 v57, v32
	s_nop 0
	v_pk_mul_f32 v[32:33], v[56:57], v[54:55]
	s_nop 0
	v_pk_mul_f32 v[16:17], v[16:17], v[32:33]
	v_lshlrev_b32_e32 v32, 16, v53
	v_mul_f32_e32 v49, 0xbfb8aa3b, v32
	v_exp_f32_e32 v49, v49
	v_and_b32_e32 v33, 0xffff0000, v53
	v_add_f32_e32 v49, 1.0, v49
	v_pk_fma_f32 v[18:19], v[18:19], v[48:49], v[34:35] op_sel_hi:[1,0,1]
	v_mul_f32_e32 v34, 0xbfb8aa3b, v33
	v_exp_f32_e32 v34, v34
	v_rcp_f32_e32 v52, v49
	v_pk_fma_f32 v[20:21], v[20:21], v[48:49], v[36:37] op_sel_hi:[1,0,1]
	v_pk_fma_f32 v[22:23], v[22:23], v[48:49], v[38:39] op_sel_hi:[1,0,1]
	v_add_f32_e32 v34, 1.0, v34
	v_rcp_f32_e32 v53, v34
	v_cvt_pk_bf16_f32 v34, v16, v17
	v_pk_fma_f32 v[24:25], v[24:25], v[48:49], v[40:41] op_sel_hi:[1,0,1]
	v_pk_fma_f32 v[28:29], v[28:29], v[48:49], v[44:45] op_sel_hi:[1,0,1]
	v_pk_mul_f32 v[32:33], v[52:53], v[32:33]
	s_nop 0
	v_pk_mul_f32 v[18:19], v[18:19], v[32:33]
	v_lshl_add_u64 v[32:33], v[158:159], 0, s[68:69]
	v_cvt_pk_bf16_f32 v35, v18, v19
	global_store_dwordx2 v[32:33], v[34:35], off offset:2048
	s_waitcnt vmcnt(3)
; __device__ __forceinline__ float bflo(unsigned u) { return __uint_as_float(u << 16); }
; __device__ __forceinline__ float bfhi(unsigned u) { return __uint_as_float(u & 0xFFFF0000u); }
; __device__ __forceinline__ float siluf_(float x) { return x * __builtin_amdgcn_rcpf(1.f + __expf(-x)); }
; __device__ __forceinline__ void ssd_pass2(const Params& p, int layer, int task, char* sm) {
;     ...
;       for (int q = 0; q < 4; q++) {
;         const int pp = 32 * wc2 + 8 * q + 4 * h5;
;         uint2 zz = *(const uint2*)(p.P + tok * PW + C_SSZ + hd * 64 + pp);
;         float v0 = (yd[4 * q] + eo * yo[4 * q]) * siluf_(bflo(zz.x));
;         float v1 = (yd[4 * q + 1] + eo * yo[4 * q + 1]) * siluf_(bfhi(zz.x));
;         float v2 = (yd[4 * q + 2] + eo * yo[4 * q + 2]) * siluf_(bflo(zz.y));
;         float v3 = (yd[4 * q + 3] + eo * yo[4 * q + 3]) * siluf_(bfhi(zz.y));
;         ss += v0 * v0 + v1 * v1 + v2 * v2 + v3 * v3;
;         *(uint2*)(p.Y + tok * YW + Y_SSD + hd * 64 + pp) = make_uint2(pk2(v0, v1), pk2(v2, v3));
;       }
;       sSsq[lp * 32 + hh * 4 + wc2 * 2 + h5] = ss;
;     }
	s_nop 3
	v_mov_b32_e32 v34, v200
	v_mov_b32_e32 v35, v201
	v_lshlrev_b32_e32 v52, 16, v34
	v_and_b32_e32 v53, 0xffff0000, v34
	v_mul_f32_e32 v34, 0xbfb8aa3b, v52
	v_exp_f32_e32 v34, v34
	s_nop 0
	v_add_f32_e32 v34, 1.0, v34
	v_rcp_f32_e32 v54, v34
	v_mul_f32_e32 v34, 0xbfb8aa3b, v53
	v_exp_f32_e32 v34, v34
	s_nop 0
	v_add_f32_e32 v34, 1.0, v34
	v_rcp_f32_e32 v55, v34
	v_lshlrev_b32_e32 v34, 16, v35
	v_and_b32_e32 v35, 0xffff0000, v35
	v_pk_mul_f32 v[36:37], v[54:55], v[52:53]
	s_nop 0
	v_pk_mul_f32 v[20:21], v[20:21], v[36:37]
	v_mul_f32_e32 v36, 0xbfb8aa3b, v34
	v_mul_f32_e32 v37, 0xbfb8aa3b, v35
	v_exp_f32_e32 v36, v36
	v_exp_f32_e32 v37, v37
	v_add_f32_e32 v36, 1.0, v36
	v_add_f32_e32 v37, 1.0, v37
	v_rcp_f32_e32 v36, v36
	v_rcp_f32_e32 v37, v37
	s_nop 0
	v_pk_mul_f32 v[34:35], v[36:37], v[34:35]
	s_nop 0
	v_pk_mul_f32 v[22:23], v[22:23], v[34:35]
	v_mov_b32_e32 v34, v16
	v_mov_b32_e32 v16, v17
	v_mov_b32_e32 v17, v21
	v_mov_b32_e32 v35, v20
	v_pk_mul_f32 v[16:17], v[16:17], v[16:17]
	s_nop 0
	v_pk_fma_f32 v[16:17], v[34:35], v[34:35], v[16:17]
	v_mov_b32_e32 v34, v18
	v_mov_b32_e32 v35, v22
	v_pk_fma_f32 v[16:17], v[34:35], v[34:35], v[16:17]
	v_mov_b32_e32 v18, v19
	v_mov_b32_e32 v19, v23
	v_pk_fma_f32 v[16:17], v[18:19], v[18:19], v[16:17]
	v_cvt_pk_bf16_f32 v18, v20, v21
	v_cvt_pk_bf16_f32 v19, v22, v23
	global_store_dwordx2 v[32:33], v[18:19], off offset:2064
	v_add_f32_e32 v16, v16, v17
	s_waitcnt vmcnt(3)
	s_nop 3
	v_mov_b32_e32 v18, v204
	v_mov_b32_e32 v19, v205
	v_lshlrev_b32_e32 v20, 16, v18
	v_and_b32_e32 v21, 0xffff0000, v18
	v_mul_f32_e32 v18, 0xbfb8aa3b, v20
	v_exp_f32_e32 v18, v18
	s_nop 0
	v_add_f32_e32 v18, 1.0, v18
	v_rcp_f32_e32 v22, v18
	v_mul_f32_e32 v18, 0xbfb8aa3b, v21
	v_exp_f32_e32 v18, v18
	s_nop 0
	v_add_f32_e32 v18, 1.0, v18
	v_rcp_f32_e32 v23, v18
	v_lshlrev_b32_e32 v18, 16, v19
	v_and_b32_e32 v19, 0xffff0000, v19
	v_pk_mul_f32 v[20:21], v[22:23], v[20:21]
	v_mul_f32_e32 v22, 0xbfb8aa3b, v18
	v_mul_f32_e32 v23, 0xbfb8aa3b, v19
	v_exp_f32_e32 v22, v22
	v_exp_f32_e32 v23, v23
	v_pk_mul_f32 v[20:21], v[24:25], v[20:21]
	v_pk_fma_f32 v[24:25], v[26:27], v[48:49], v[42:43] op_sel_hi:[1,0,1]
	v_add_f32_e32 v22, 1.0, v22
	v_add_f32_e32 v23, 1.0, v23
	v_rcp_f32_e32 v22, v22
	v_rcp_f32_e32 v23, v23
	s_nop 0
	v_pk_mul_f32 v[18:19], v[22:23], v[18:19]
	s_nop 0
	v_pk_mul_f32 v[18:19], v[24:25], v[18:19]
	v_cvt_pk_bf16_f32 v22, v20, v21
	v_cvt_pk_bf16_f32 v23, v18, v19
	global_store_dwordx2 v[32:33], v[22:23], off offset:2080
	s_waitcnt vmcnt(3)
	s_nop 3
	v_mov_b32_e32 v22, v210
	v_mov_b32_e32 v23, v211
	v_lshlrev_b32_e32 v24, 16, v22
	v_and_b32_e32 v25, 0xffff0000, v22
	v_mul_f32_e32 v22, 0xbfb8aa3b, v24
	v_exp_f32_e32 v22, v22
	s_nop 0
	v_add_f32_e32 v22, 1.0, v22
	v_rcp_f32_e32 v26, v22
	v_mul_f32_e32 v22, 0xbfb8aa3b, v25
	v_exp_f32_e32 v22, v22
	s_nop 0
	v_add_f32_e32 v22, 1.0, v22
	v_rcp_f32_e32 v27, v22
	v_lshlrev_b32_e32 v22, 16, v23
	v_and_b32_e32 v23, 0xffff0000, v23
	v_pk_mul_f32 v[24:25], v[26:27], v[24:25]
	v_mul_f32_e32 v26, 0xbfb8aa3b, v22
	v_mul_f32_e32 v27, 0xbfb8aa3b, v23
	v_exp_f32_e32 v26, v26
	v_exp_f32_e32 v27, v27
	v_pk_mul_f32 v[24:25], v[28:29], v[24:25]
	v_pk_fma_f32 v[28:29], v[30:31], v[48:49], v[46:47] op_sel_hi:[1,0,1]
	v_add_f32_e32 v26, 1.0, v26
	v_add_f32_e32 v27, 1.0, v27
	v_rcp_f32_e32 v26, v26
	v_rcp_f32_e32 v27, v27
	s_nop 0
	v_pk_mul_f32 v[22:23], v[26:27], v[22:23]
	v_mov_b32_e32 v26, v20
	v_mov_b32_e32 v20, v21
	v_mov_b32_e32 v21, v25
	v_pk_mul_f32 v[22:23], v[28:29], v[22:23]
	v_mov_b32_e32 v27, v24
	v_pk_mul_f32 v[20:21], v[20:21], v[20:21]
	v_cvt_pk_bf16_f32 v17, v22, v23
	v_pk_fma_f32 v[20:21], v[26:27], v[26:27], v[20:21]
	v_mov_b32_e32 v26, v18
	v_mov_b32_e32 v27, v22
	v_pk_fma_f32 v[20:21], v[26:27], v[26:27], v[20:21]
	v_mov_b32_e32 v18, v19
	v_mov_b32_e32 v19, v23
	v_pk_fma_f32 v[18:19], v[18:19], v[18:19], v[20:21]
	s_nop 0
	v_add_f32_e32 v16, v16, v18
	v_add_f32_e32 v18, v16, v19
	v_cvt_pk_bf16_f32 v16, v24, v25
	global_store_dwordx2 v[32:33], v[16:17], off offset:2096
	v_lshl_add_u32 v16, s86, 4, v247
	s_add_i32 s86, s86, 1
	s_cmp_eq_u32 s86, 8
	ds_write_b32 v16, v18 offset:60416
	s_cbranch_scc0 .LBB0_1872
	s_branch .LBB0_2033

; __device__ __forceinline__ float bflo(unsigned u) { return __uint_as_float(u << 16); }
; __device__ __forceinline__ float bfhi(unsigned u) { return __uint_as_float(u & 0xFFFF0000u); }
; __device__ __forceinline__ float siluf_(float x) { return x * __builtin_amdgcn_rcpf(1.f + __expf(-x)); }
; __device__ __forceinline__ f32x16 mfma32(bf16x8 a, bf16x8 b, f32x16 c) { return __builtin_amdgcn_mfma_f32_32x32x16_bf16(a, b, c, 0, 0, 0); }
; __device__ __forceinline__ void ssd_pass2(const Params& p, int layer, int task, char* sm) {
;     ...
;     const int nks = nS >> 4;
;     for (int ks = 0; ks < nks; ks++) {
;       bf16x8 xf = *(const bf16x8*)(sXT + (32 * wc2 + r32) * 136 + ks * 16 + 8 * h5);
;       bf16x8 mf = *(const bf16x8*)(sM + (32 * wr + r32) * 136 + ks * 16 + 8 * h5);
;       yd = mfma32(xf, mf, yd);
;     }
;     {
; #pragma unroll
;       for (int ks = 0; ks < 8; ks++) {
;         bf16x8 cf = *(const bf16x8*)(sC + (32 * wr + r32) * 136 + ks * 16 + 8 * h5);
;         yo = mfma32(pfr[ks], cf, yo);
;       }
;     }
;     {
;       const int lp = 32 * wr + r32; const int l = 64 * lh + lp; const size_t tok = tok0 + l;
;       const float eo = __expf(sAcs[l * 8 + hh]);
;       float ss = 0.f;
; #pragma unroll
;       for (int q = 0; q < 4; q++) {
;         const int pp = 32 * wc2 + 8 * q + 4 * h5;
;         uint2 zz = *(const uint2*)(p.P + tok * PW + C_SSZ + hd * 64 + pp);
;         float v0 = (yd[4 * q] + eo * yo[4 * q]) * siluf_(bflo(zz.x));
;         float v1 = (yd[4 * q + 1] + eo * yo[4 * q + 1]) * siluf_(bfhi(zz.x));
;         float v2 = (yd[4 * q + 2] + eo * yo[4 * q + 2]) * siluf_(bflo(zz.y));
.LBB0_2269:
	v_mov_b32_e32 v16, v145
	v_mov_b32_e32 v17, v145
	v_mov_b32_e32 v18, v145
	v_mov_b32_e32 v19, v145
	v_mov_b32_e32 v20, v145
	v_mov_b32_e32 v21, v145
	v_mov_b32_e32 v22, v145
	v_mov_b32_e32 v23, v145
	v_mov_b32_e32 v24, v145
	v_mov_b32_e32 v25, v145
	v_mov_b32_e32 v26, v145
	v_mov_b32_e32 v27, v145
	v_mov_b32_e32 v28, v145
	v_mov_b32_e32 v29, v145
	v_mov_b32_e32 v30, v145
	v_mov_b32_e32 v31, v145
	s_waitcnt lgkmcnt(0)
	s_barrier
	v_lshl_add_u64 v[250:251], s[68:69], 1, v[156:157]
	global_load_dwordx2 v[170:171], v[250:251], off
	global_load_dwordx2 v[172:173], v[250:251], off offset:16
	global_load_dwordx2 v[204:205], v[250:251], off offset:32
	global_load_dwordx2 v[210:211], v[250:251], off offset:48
	s_mov_b32 s78, 0
	v_mov_b64_e32 v[46:47], v[30:31]
	v_mov_b32_e32 v144, v249
	v_mov_b32_e32 v160, v248
	v_mov_b64_e32 v[44:45], v[28:29]
	v_mov_b64_e32 v[42:43], v[26:27]
	v_mov_b64_e32 v[40:41], v[24:25]
	v_mov_b64_e32 v[38:39], v[22:23]
	v_mov_b64_e32 v[36:37], v[20:21]
	v_mov_b64_e32 v[34:35], v[18:19]
	v_mov_b64_e32 v[32:33], v[16:17]
.LBB0_2270:
	ds_read_b128 v[162:165], v144
	ds_read_b128 v[166:169], v160
	s_add_i32 s78, s78, 1
	v_add_u32_e32 v160, 32, v160
	s_cmp_ge_u32 s78, s85
	v_add_u32_e32 v144, 32, v144
	s_waitcnt lgkmcnt(0)
	v_mfma_f32_32x32x16_bf16 v[32:47], v[162:165], v[166:169], v[32:47]
	s_cbranch_scc0 .LBB0_2270
	v_cvt_pk_bf16_f32 v108, v108, v109
	v_cvt_pk_bf16_f32 v109, v110, v111
	v_cvt_pk_bf16_f32 v110, v100, v101
	v_cvt_pk_bf16_f32 v111, v102, v103
	v_cvt_pk_bf16_f32 v103, v94, v95
	v_cvt_pk_bf16_f32 v95, v86, v87
	v_cvt_pk_bf16_f32 v87, v78, v79
	v_cvt_pk_bf16_f32 v79, v70, v71
	v_cvt_pk_bf16_f32 v71, v62, v63
	v_cvt_pk_bf16_f32 v62, v52, v53
	v_cvt_pk_bf16_f32 v63, v54, v55
	v_cvt_pk_bf16_f32 v52, v56, v57
	v_cvt_pk_bf16_f32 v53, v58, v59
	v_cvt_pk_bf16_f32 v54, v48, v49
	v_cvt_pk_bf16_f32 v55, v50, v51
	ds_read_b128 v[48:51], v188 offset:8192
	ds_read_b128 v[56:59], v188 offset:8224
	s_waitcnt lgkmcnt(1)
	v_mfma_f32_32x32x16_bf16 v[16:31], v[108:111], v[48:51], v[16:31]
	v_cvt_pk_bf16_f32 v100, v104, v105
	v_cvt_pk_bf16_f32 v101, v106, v107
	v_cvt_pk_bf16_f32 v102, v92, v93
	v_cvt_pk_bf16_f32 v92, v96, v97
	v_cvt_pk_bf16_f32 v93, v98, v99
	v_cvt_pk_bf16_f32 v94, v84, v85
	ds_read_b128 v[48:51], v188 offset:8256
	s_waitcnt lgkmcnt(1)
	v_mfma_f32_32x32x16_bf16 v[16:31], v[100:103], v[56:59], v[16:31]
	v_cvt_pk_bf16_f32 v84, v88, v89
	v_cvt_pk_bf16_f32 v85, v90, v91
	v_cvt_pk_bf16_f32 v86, v76, v77
	v_cvt_pk_bf16_f32 v76, v80, v81
	v_cvt_pk_bf16_f32 v77, v82, v83
	v_cvt_pk_bf16_f32 v78, v68, v69
	v_cvt_pk_bf16_f32 v68, v72, v73
	s_waitcnt lgkmcnt(0)
	v_mfma_f32_32x32x16_bf16 v[16:31], v[92:95], v[48:51], v[16:31]
	ds_read_b128 v[48:51], v188 offset:8288
	v_cvt_pk_bf16_f32 v69, v74, v75
	v_cvt_pk_bf16_f32 v70, v60, v61
	v_cvt_pk_bf16_f32 v60, v64, v65
	v_cvt_pk_bf16_f32 v61, v66, v67
	s_lshl_b32 s68, s68, 1
	s_waitcnt lgkmcnt(0)
	v_mfma_f32_32x32x16_bf16 v[16:31], v[84:87], v[48:51], v[16:31]
	ds_read_b128 v[48:51], v188 offset:8320
	s_waitcnt lgkmcnt(0)
	v_mfma_f32_32x32x16_bf16 v[16:31], v[76:79], v[48:51], v[16:31]
	ds_read_b128 v[48:51], v188 offset:8352
	s_waitcnt lgkmcnt(0)
	v_mfma_f32_32x32x16_bf16 v[16:31], v[68:71], v[48:51], v[16:31]
	ds_read_b128 v[48:51], v188 offset:8384
	s_waitcnt lgkmcnt(0)
	v_mfma_f32_32x32x16_bf16 v[16:31], v[60:63], v[48:51], v[16:31]
	ds_read_b128 v[48:51], v188 offset:8416
	s_waitcnt lgkmcnt(0)
	v_mfma_f32_32x32x16_bf16 v[16:31], v[52:55], v[48:51], v[16:31]
	v_lshl_add_u64 v[50:51], v[156:157], 0, s[68:69]
	v_lshl_add_u32 v48, s86, 2, v246
	ds_read_b32 v48, v48
	s_waitcnt lgkmcnt(0)
	v_mul_f32_e32 v48, 0x3fb8aa3b, v48
	v_exp_f32_e32 v48, v48
	s_waitcnt vmcnt(3)
	v_mov_b32_e32 v52, v170
	v_mov_b32_e32 v53, v171
	v_lshlrev_b32_e32 v54, 16, v52
	v_mul_f32_e32 v49, 0xbfb8aa3b, v54
	v_exp_f32_e32 v49, v49
	v_and_b32_e32 v55, 0xffff0000, v52
	v_add_f32_e32 v49, 1.0, v49
	v_pk_fma_f32 v[16:17], v[16:17], v[48:49], v[32:33] op_sel_hi:[1,0,1]
	v_mul_f32_e32 v32, 0xbfb8aa3b, v55
	v_exp_f32_e32 v32, v32
	v_rcp_f32_e32 v56, v49
	v_add_f32_e32 v32, 1.0, v32
	v_rcp_f32_e32 v57, v32
	s_nop 0
	v_pk_mul_f32 v[32:33], v[56:57], v[54:55]
	s_nop 0
	v_pk_mul_f32 v[16:17], v[16:17], v[32:33]
	v_lshlrev_b32_e32 v32, 16, v53
	v_mul_f32_e32 v49, 0xbfb8aa3b, v32
	v_exp_f32_e32 v49, v49
	v_and_b32_e32 v33, 0xffff0000, v53
	v_add_f32_e32 v49, 1.0, v49
	v_pk_fma_f32 v[18:19], v[18:19], v[48:49], v[34:35] op_sel_hi:[1,0,1]
	v_mul_f32_e32 v34, 0xbfb8aa3b, v33
	v_exp_f32_e32 v34, v34
	v_rcp_f32_e32 v52, v49
	v_pk_fma_f32 v[20:21], v[20:21], v[48:49], v[36:37] op_sel_hi:[1,0,1]
	v_pk_fma_f32 v[22:23], v[22:23], v[48:49], v[38:39] op_sel_hi:[1,0,1]
	v_add_f32_e32 v34, 1.0, v34
	v_rcp_f32_e32 v53, v34
	v_cvt_pk_bf16_f32 v34, v16, v17
	v_pk_fma_f32 v[24:25], v[24:25], v[48:49], v[40:41] op_sel_hi:[1,0,1]
	v_pk_fma_f32 v[28:29], v[28:29], v[48:49], v[44:45] op_sel_hi:[1,0,1]
	v_pk_mul_f32 v[32:33], v[52:53], v[32:33]
	s_nop 0
	v_pk_mul_f32 v[18:19], v[18:19], v[32:33]
	v_lshl_add_u64 v[32:33], v[158:159], 0, s[68:69]
	v_cvt_pk_bf16_f32 v35, v18, v19
	global_store_dwordx2 v[32:33], v[34:35], off offset:2048
	s_waitcnt vmcnt(3)
; __device__ __forceinline__ float bflo(unsigned u) { return __uint_as_float(u << 16); }
; __device__ __forceinline__ float bfhi(unsigned u) { return __uint_as_float(u & 0xFFFF0000u); }
; __device__ __forceinline__ float siluf_(float x) { return x * __builtin_amdgcn_rcpf(1.f + __expf(-x)); }
; __device__ __forceinline__ void ssd_pass2(const Params& p, int layer, int task, char* sm) {
;     ...
;       for (int q = 0; q < 4; q++) {
;         const int pp = 32 * wc2 + 8 * q + 4 * h5;
;         uint2 zz = *(const uint2*)(p.P + tok * PW + C_SSZ + hd * 64 + pp);
;         float v0 = (yd[4 * q] + eo * yo[4 * q]) * siluf_(bflo(zz.x));
;         float v1 = (yd[4 * q + 1] + eo * yo[4 * q + 1]) * siluf_(bfhi(zz.x));
;         float v2 = (yd[4 * q + 2] + eo * yo[4 * q + 2]) * siluf_(bflo(zz.y));
;         float v3 = (yd[4 * q + 3] + eo * yo[4 * q + 3]) * siluf_(bfhi(zz.y));
;         ss += v0 * v0 + v1 * v1 + v2 * v2 + v3 * v3;
;         *(uint2*)(p.Y + tok * YW + Y_SSD + hd * 64 + pp) = make_uint2(pk2(v0, v1), pk2(v2, v3));
;       }
;       sSsq[lp * 32 + hh * 4 + wc2 * 2 + h5] = ss;
;     }
	s_nop 3
	v_mov_b32_e32 v34, v172
	v_mov_b32_e32 v35, v173
	v_lshlrev_b32_e32 v52, 16, v34
	v_and_b32_e32 v53, 0xffff0000, v34
	v_mul_f32_e32 v34, 0xbfb8aa3b, v52
	v_exp_f32_e32 v34, v34
	s_nop 0
	v_add_f32_e32 v34, 1.0, v34
	v_rcp_f32_e32 v54, v34
	v_mul_f32_e32 v34, 0xbfb8aa3b, v53
	v_exp_f32_e32 v34, v34
	s_nop 0
	v_add_f32_e32 v34, 1.0, v34
	v_rcp_f32_e32 v55, v34
	v_lshlrev_b32_e32 v34, 16, v35
	v_and_b32_e32 v35, 0xffff0000, v35
	v_pk_mul_f32 v[36:37], v[54:55], v[52:53]
	s_nop 0
	v_pk_mul_f32 v[20:21], v[20:21], v[36:37]
	v_mul_f32_e32 v36, 0xbfb8aa3b, v34
	v_mul_f32_e32 v37, 0xbfb8aa3b, v35
	v_exp_f32_e32 v36, v36
	v_exp_f32_e32 v37, v37
	v_add_f32_e32 v36, 1.0, v36
	v_add_f32_e32 v37, 1.0, v37
	v_rcp_f32_e32 v36, v36
	v_rcp_f32_e32 v37, v37
	s_nop 0
	v_pk_mul_f32 v[34:35], v[36:37], v[34:35]
	s_nop 0
	v_pk_mul_f32 v[22:23], v[22:23], v[34:35]
	v_mov_b32_e32 v34, v16
	v_mov_b32_e32 v16, v17
	v_mov_b32_e32 v17, v21
	v_mov_b32_e32 v35, v20
	v_pk_mul_f32 v[16:17], v[16:17], v[16:17]
	s_nop 0
	v_pk_fma_f32 v[16:17], v[34:35], v[34:35], v[16:17]
	v_mov_b32_e32 v34, v18
	v_mov_b32_e32 v35, v22
	v_pk_fma_f32 v[16:17], v[34:35], v[34:35], v[16:17]
	v_mov_b32_e32 v18, v19
	v_mov_b32_e32 v19, v23
	v_pk_fma_f32 v[16:17], v[18:19], v[18:19], v[16:17]
	v_cvt_pk_bf16_f32 v18, v20, v21
	v_cvt_pk_bf16_f32 v19, v22, v23
	global_store_dwordx2 v[32:33], v[18:19], off offset:2064
	v_add_f32_e32 v16, v16, v17
	s_waitcnt vmcnt(3)
	s_nop 3
	v_mov_b32_e32 v18, v204
	v_mov_b32_e32 v19, v205
	v_lshlrev_b32_e32 v20, 16, v18
	v_and_b32_e32 v21, 0xffff0000, v18
	v_mul_f32_e32 v18, 0xbfb8aa3b, v20
	v_exp_f32_e32 v18, v18
	s_nop 0
	v_add_f32_e32 v18, 1.0, v18
	v_rcp_f32_e32 v22, v18
	v_mul_f32_e32 v18, 0xbfb8aa3b, v21
	v_exp_f32_e32 v18, v18
	s_nop 0
	v_add_f32_e32 v18, 1.0, v18
	v_rcp_f32_e32 v23, v18
	v_lshlrev_b32_e32 v18, 16, v19
	v_and_b32_e32 v19, 0xffff0000, v19
	v_pk_mul_f32 v[20:21], v[22:23], v[20:21]
	v_mul_f32_e32 v22, 0xbfb8aa3b, v18
	v_mul_f32_e32 v23, 0xbfb8aa3b, v19
	v_exp_f32_e32 v22, v22
	v_exp_f32_e32 v23, v23
	v_pk_mul_f32 v[20:21], v[24:25], v[20:21]
	v_pk_fma_f32 v[24:25], v[26:27], v[48:49], v[42:43] op_sel_hi:[1,0,1]
	v_add_f32_e32 v22, 1.0, v22
	v_add_f32_e32 v23, 1.0, v23
	v_rcp_f32_e32 v22, v22
	v_rcp_f32_e32 v23, v23
	s_nop 0
	v_pk_mul_f32 v[18:19], v[22:23], v[18:19]
	s_nop 0
	v_pk_mul_f32 v[18:19], v[24:25], v[18:19]
	v_cvt_pk_bf16_f32 v22, v20, v21
	v_cvt_pk_bf16_f32 v23, v18, v19
	global_store_dwordx2 v[32:33], v[22:23], off offset:2080
	s_waitcnt vmcnt(3)
	s_nop 3
	v_mov_b32_e32 v22, v210
	v_mov_b32_e32 v23, v211
	v_lshlrev_b32_e32 v24, 16, v22
	v_and_b32_e32 v25, 0xffff0000, v22
	v_mul_f32_e32 v22, 0xbfb8aa3b, v24
	v_exp_f32_e32 v22, v22
	s_nop 0
	v_add_f32_e32 v22, 1.0, v22
	v_rcp_f32_e32 v26, v22
	v_mul_f32_e32 v22, 0xbfb8aa3b, v25
	v_exp_f32_e32 v22, v22
	s_nop 0
	v_add_f32_e32 v22, 1.0, v22
	v_rcp_f32_e32 v27, v22
	v_lshlrev_b32_e32 v22, 16, v23
	v_and_b32_e32 v23, 0xffff0000, v23
	v_pk_mul_f32 v[24:25], v[26:27], v[24:25]
	v_mul_f32_e32 v26, 0xbfb8aa3b, v22
	v_mul_f32_e32 v27, 0xbfb8aa3b, v23
	v_exp_f32_e32 v26, v26
	v_exp_f32_e32 v27, v27
	v_pk_mul_f32 v[24:25], v[28:29], v[24:25]
	v_pk_fma_f32 v[28:29], v[30:31], v[48:49], v[46:47] op_sel_hi:[1,0,1]
	v_add_f32_e32 v26, 1.0, v26
	v_add_f32_e32 v27, 1.0, v27
	v_rcp_f32_e32 v26, v26
	v_rcp_f32_e32 v27, v27
	s_nop 0
	v_pk_mul_f32 v[22:23], v[26:27], v[22:23]
	v_mov_b32_e32 v26, v20
	v_mov_b32_e32 v20, v21
	v_mov_b32_e32 v21, v25
	v_pk_mul_f32 v[22:23], v[28:29], v[22:23]
	v_mov_b32_e32 v27, v24
	v_pk_mul_f32 v[20:21], v[20:21], v[20:21]
	v_cvt_pk_bf16_f32 v17, v22, v23
	v_pk_fma_f32 v[20:21], v[26:27], v[26:27], v[20:21]
	v_mov_b32_e32 v26, v18
	v_mov_b32_e32 v27, v22
	v_pk_fma_f32 v[20:21], v[26:27], v[26:27], v[20:21]
	v_mov_b32_e32 v18, v19
	v_mov_b32_e32 v19, v23
	v_pk_fma_f32 v[18:19], v[18:19], v[18:19], v[20:21]
	s_nop 0
	v_add_f32_e32 v16, v16, v18
	v_add_f32_e32 v18, v16, v19
	v_cvt_pk_bf16_f32 v16, v24, v25
	global_store_dwordx2 v[32:33], v[16:17], off offset:2096
	v_lshl_add_u32 v16, s86, 4, v247
	s_add_i32 s86, s86, 1
	s_cmp_eq_u32 s86, 8
	ds_write_b32 v16, v18 offset:60416
	s_cbranch_scc0 .LBB0_2118
	s_branch .LBB0_2279
